# out-projection: final LayerNorm output rows stored with the nt (streaming) hint
# baseline (speedup 1.0000x reference)
.LBB0_1048:
	v_lshl_add_u64 v[12:13], v[8:9], 0, v[110:111]
	v_lshl_add_u64 v[30:31], v[20:21], 0, v[110:111]
	v_lshl_add_u64 v[28:29], v[18:19], 0, v[110:111]
	v_lshl_add_u64 v[26:27], v[16:17], 0, v[110:111]
	v_lshl_add_u64 v[14:15], v[10:11], 0, v[110:111]
	flat_load_dwordx4 v[0:3], v[22:23]
	flat_load_dwordx4 v[4:7], v[24:25]
	flat_load_dwordx4 v[32:35], v[12:13]
	flat_load_dwordx4 v[36:39], v[12:13] offset:1024
	flat_load_dwordx4 v[40:43], v[12:13] offset:2048
	flat_load_dwordx4 v[44:47], v[12:13] offset:3072
	flat_load_dwordx4 v[48:51], v[30:31]
	flat_load_dwordx4 v[52:55], v[28:29]
	flat_load_dwordx4 v[56:59], v[26:27]
	flat_load_dwordx4 v[60:63], v[14:15]
	s_add_i32 s3, s3, 2
	v_lshl_add_u64 v[8:9], v[8:9], 0, s[30:31]
	v_lshl_add_u64 v[10:11], v[10:11], 0, s[30:31]
	v_lshl_add_u64 v[16:17], v[16:17], 0, s[30:31]
	v_lshl_add_u64 v[18:19], v[18:19], 0, s[30:31]
	v_lshl_add_u64 v[20:21], v[20:21], 0, s[30:31]
	s_cmp_gt_u32 s3, 13
	s_waitcnt vmcnt(0) lgkmcnt(0)
	v_mov_b32_e32 v70, v33
	v_mov_b32_e32 v71, v34
	v_mov_b32_e32 v72, v32
	v_mov_b32_e32 v73, v35
	v_mov_b32_e32 v74, v37
	v_mov_b32_e32 v75, v38
	v_mov_b32_e32 v76, v36
	v_mov_b32_e32 v77, v39
	v_add_f32_e32 v78, v40, v41
	v_add_f32_e32 v80, v42, v43
	v_mov_b32_e32 v79, v46
	v_mov_b32_e32 v81, v47
	v_mov_b32_e32 v84, v49
	v_mov_b32_e32 v85, v50
	v_mov_b32_e32 v86, v48
	v_mov_b32_e32 v87, v51
	v_mov_b32_e32 v88, v53
	v_mov_b32_e32 v89, v54
	v_mov_b32_e32 v90, v52
	v_mov_b32_e32 v91, v55
	v_pk_add_f32 v[70:71], v[70:71], v[72:73]
	v_pk_add_f32 v[72:73], v[74:75], v[76:77]
	v_pk_add_f32 v[74:75], v[78:79], v[80:81]
	v_pk_add_f32 v[76:77], v[84:85], v[86:87]
	v_pk_add_f32 v[78:79], v[88:89], v[90:91]
	v_add_f32_e32 v82, v70, v71
	v_pk_add_f32 v[70:71], v[72:73], v[72:73] op_sel:[0,1] op_sel_hi:[1,0]
	v_add_f32_e32 v76, v76, v77
	v_pk_add_f32 v[72:73], v[78:79], v[78:79] op_sel:[0,1] op_sel_hi:[1,0]
	v_mov_b32_e32 v83, v44
	v_add_f32_e32 v92, v56, v57
	v_add_f32_e32 v94, v58, v59
	v_mov_b32_e32 v97, v60
	v_mov_b32_e32 v93, v62
	v_mov_b32_e32 v95, v63
	v_add_f32_e32 v82, 0, v82
	v_mov_b32_e32 v71, v45
	v_add_f32_e32 v96, 0, v76
	v_mov_b32_e32 v73, v61
	v_pk_add_f32 v[80:81], v[92:93], v[94:95]
	v_pk_add_f32 v[70:71], v[82:83], v[70:71]
	v_pk_add_f32 v[72:73], v[96:97], v[72:73]
	v_pk_add_f32 v[70:71], v[70:71], v[74:75]
	v_pk_add_f32 v[72:73], v[72:73], v[80:81]
	v_add_f32_e32 v70, v70, v71
	v_add_f32_e32 v71, v72, v73
	ds_bpermute_b32 v72, v205, v70
	ds_bpermute_b32 v73, v205, v71
	s_waitcnt lgkmcnt(1)
	v_add_f32_e32 v70, v70, v72
	s_waitcnt lgkmcnt(0)
	v_add_f32_e32 v71, v71, v73
	ds_bpermute_b32 v72, v206, v70
	ds_bpermute_b32 v73, v206, v71
	s_waitcnt lgkmcnt(1)
	v_add_f32_e32 v70, v70, v72
	s_waitcnt lgkmcnt(0)
	v_add_f32_e32 v71, v71, v73
	ds_bpermute_b32 v72, v207, v70
	ds_bpermute_b32 v73, v207, v71
	s_waitcnt lgkmcnt(1)
	v_add_f32_e32 v70, v70, v72
	s_waitcnt lgkmcnt(0)
	v_add_f32_e32 v71, v71, v73
	ds_bpermute_b32 v72, v208, v70
	ds_bpermute_b32 v73, v208, v71
	s_waitcnt lgkmcnt(1)
	v_add_f32_e32 v70, v70, v72
	s_waitcnt lgkmcnt(0)
	v_add_f32_e32 v71, v71, v73
	ds_bpermute_b32 v72, v209, v70
	ds_bpermute_b32 v73, v209, v71
	s_waitcnt lgkmcnt(1)
	v_add_f32_e32 v70, v70, v72
	s_waitcnt lgkmcnt(0)
	v_add_f32_e32 v71, v71, v73
	ds_bpermute_b32 v72, v210, v70
	ds_bpermute_b32 v73, v210, v71
	s_waitcnt lgkmcnt(1)
	v_add_f32_e32 v70, v70, v72
	s_waitcnt lgkmcnt(0)
	v_add_f32_e32 v71, v71, v73
	v_mul_f32_e32 v70, 0x3a800000, v70
	v_mul_f32_e32 v72, 0x3a800000, v71
	v_pk_add_f32 v[32:33], v[32:33], v[70:71] op_sel_hi:[1,0] neg_lo:[0,1] neg_hi:[0,1]
	v_pk_add_f32 v[34:35], v[34:35], v[70:71] op_sel_hi:[1,0] neg_lo:[0,1] neg_hi:[0,1]
	v_pk_add_f32 v[48:49], v[48:49], v[72:73] op_sel_hi:[1,0] neg_lo:[0,1] neg_hi:[0,1]
	v_pk_add_f32 v[50:51], v[50:51], v[72:73] op_sel_hi:[1,0] neg_lo:[0,1] neg_hi:[0,1]
	v_pk_add_f32 v[36:37], v[36:37], v[70:71] op_sel_hi:[1,0] neg_lo:[0,1] neg_hi:[0,1]
	v_pk_add_f32 v[38:39], v[38:39], v[70:71] op_sel_hi:[1,0] neg_lo:[0,1] neg_hi:[0,1]
	v_pk_add_f32 v[52:53], v[52:53], v[72:73] op_sel_hi:[1,0] neg_lo:[0,1] neg_hi:[0,1]
	v_pk_add_f32 v[54:55], v[54:55], v[72:73] op_sel_hi:[1,0] neg_lo:[0,1] neg_hi:[0,1]
	v_pk_add_f32 v[56:57], v[56:57], v[72:73] op_sel_hi:[1,0] neg_lo:[0,1] neg_hi:[0,1]
	v_pk_add_f32 v[58:59], v[58:59], v[72:73] op_sel_hi:[1,0] neg_lo:[0,1] neg_hi:[0,1]
	v_pk_add_f32 v[60:61], v[60:61], v[72:73] op_sel_hi:[1,0] neg_lo:[0,1] neg_hi:[0,1]
	v_pk_add_f32 v[62:63], v[62:63], v[72:73] op_sel_hi:[1,0] neg_lo:[0,1] neg_hi:[0,1]
	v_mov_b32_e32 v72, v33
	v_mov_b32_e32 v73, v35
	v_mov_b32_e32 v76, v49
	v_mov_b32_e32 v77, v51
	v_mov_b32_e32 v80, v37
	v_mov_b32_e32 v81, v39
	v_mov_b32_e32 v84, v53
	v_mov_b32_e32 v85, v55
	v_pk_add_f32 v[40:41], v[40:41], v[70:71] op_sel_hi:[1,0] neg_lo:[0,1] neg_hi:[0,1]
	v_pk_add_f32 v[42:43], v[42:43], v[70:71] op_sel_hi:[1,0] neg_lo:[0,1] neg_hi:[0,1]
	v_pk_add_f32 v[44:45], v[44:45], v[70:71] op_sel_hi:[1,0] neg_lo:[0,1] neg_hi:[0,1]
	v_pk_add_f32 v[46:47], v[46:47], v[70:71] op_sel_hi:[1,0] neg_lo:[0,1] neg_hi:[0,1]
	v_mov_b32_e32 v70, v32
	v_mov_b32_e32 v71, v34
	v_mov_b32_e32 v74, v48
	v_mov_b32_e32 v75, v50
	v_mov_b32_e32 v78, v36
	v_mov_b32_e32 v79, v38
	v_mov_b32_e32 v82, v52
	v_mov_b32_e32 v83, v54
	v_pk_mul_f32 v[72:73], v[72:73], v[72:73]
	v_pk_mul_f32 v[76:77], v[76:77], v[76:77]
	v_pk_mul_f32 v[80:81], v[80:81], v[80:81]
	v_pk_mul_f32 v[84:85], v[84:85], v[84:85]
	v_mul_f32_e32 v86, v40, v40
	v_mul_f32_e32 v88, v42, v42
	v_mul_f32_e32 v90, v56, v56
	v_mul_f32_e32 v92, v58, v58
	v_pk_fma_f32 v[70:71], v[70:71], v[70:71], v[72:73]
	v_pk_fma_f32 v[72:73], v[74:75], v[74:75], v[76:77]
	v_pk_fma_f32 v[74:75], v[78:79], v[78:79], v[80:81]
	v_pk_fma_f32 v[76:77], v[82:83], v[82:83], v[84:85]
	v_pk_mul_f32 v[94:95], v[44:45], v[44:45]
	v_pk_mul_f32 v[96:97], v[46:47], v[46:47]
	v_pk_mul_f32 v[98:99], v[60:61], v[60:61]
	v_pk_mul_f32 v[100:101], v[62:63], v[62:63]
	v_pk_fma_f32 v[86:87], v[40:41], v[40:41], v[86:87] op_sel_hi:[1,1,0]
	v_pk_fma_f32 v[88:89], v[42:43], v[42:43], v[88:89] op_sel_hi:[1,1,0]
	v_pk_fma_f32 v[90:91], v[56:57], v[56:57], v[90:91] op_sel_hi:[1,1,0]
	v_pk_fma_f32 v[92:93], v[58:59], v[58:59], v[92:93] op_sel_hi:[1,1,0]
	v_pk_add_f32 v[70:71], v[70:71], v[70:71] op_sel_hi:[0,1]
	v_pk_add_f32 v[72:73], v[72:73], v[72:73] op_sel_hi:[0,1]
	v_pk_add_f32 v[74:75], v[74:75], v[74:75] op_sel_hi:[0,1]
	v_pk_add_f32 v[76:77], v[76:77], v[76:77] op_sel_hi:[0,1]
	v_mov_b32_e32 v86, v94
	v_mov_b32_e32 v88, v95
	v_mov_b32_e32 v90, v98
	v_mov_b32_e32 v92, v99
	v_mov_b32_e32 v70, v96
	v_mov_b32_e32 v74, v97
	v_mov_b32_e32 v72, v100
	v_mov_b32_e32 v76, v101
	v_pk_add_f32 v[78:79], v[86:87], v[88:89]
	v_pk_add_f32 v[80:81], v[90:91], v[92:93]
	v_pk_add_f32 v[70:71], v[70:71], v[74:75]
	v_pk_add_f32 v[72:73], v[72:73], v[76:77]
	v_pk_add_f32 v[70:71], v[78:79], v[70:71]
	v_pk_add_f32 v[72:73], v[80:81], v[72:73]
	v_mov_b32_e32 v75, v70
	v_mov_b32_e32 v74, v72
	v_mov_b32_e32 v70, v73
	v_pk_add_f32 v[70:71], v[74:75], v[70:71]
	ds_bpermute_b32 v73, v205, v71
	ds_bpermute_b32 v72, v205, v70
	s_waitcnt lgkmcnt(0)
	v_pk_add_f32 v[70:71], v[70:71], v[72:73]
	ds_bpermute_b32 v73, v206, v71
	ds_bpermute_b32 v72, v206, v70
	s_waitcnt lgkmcnt(0)
	v_pk_add_f32 v[70:71], v[70:71], v[72:73]
	ds_bpermute_b32 v73, v207, v71
	ds_bpermute_b32 v72, v207, v70
	s_waitcnt lgkmcnt(0)
	v_pk_add_f32 v[70:71], v[70:71], v[72:73]
	ds_bpermute_b32 v73, v208, v71
	ds_bpermute_b32 v72, v208, v70
	s_waitcnt lgkmcnt(0)
	v_pk_add_f32 v[70:71], v[70:71], v[72:73]
	ds_bpermute_b32 v73, v209, v71
	ds_bpermute_b32 v72, v209, v70
	s_waitcnt lgkmcnt(0)
	v_pk_add_f32 v[70:71], v[70:71], v[72:73]
	ds_bpermute_b32 v73, v210, v71
	ds_bpermute_b32 v72, v210, v70
	s_waitcnt lgkmcnt(0)
	v_pk_add_f32 v[70:71], v[70:71], v[72:73]
	s_nop 0
	v_pk_fma_f32 v[70:71], v[70:71], s[28:29], v[188:189] op_sel_hi:[1,0,0]
	s_nop 0
	v_mul_f32_e32 v72, 0x4b800000, v71
	v_cmp_gt_f32_e64 s[0:1], s40, v71
	v_mul_f32_e32 v73, 0x4b800000, v70
	v_cmp_gt_f32_e32 vcc, s40, v70
	v_cndmask_b32_e64 v71, v71, v72, s[0:1]
	v_rsq_f32_e32 v71, v71
	v_cndmask_b32_e32 v70, v70, v73, vcc
	v_rsq_f32_e32 v72, v70
	v_mul_f32_e32 v70, 0x45800000, v71
	v_cndmask_b32_e64 v70, v71, v70, s[0:1]
	v_mul_f32_e32 v73, 0x45800000, v72
	v_cndmask_b32_e32 v72, v72, v73, vcc
	v_pk_mul_f32 v[32:33], v[32:33], v[70:71] op_sel_hi:[1,0]
	v_pk_mul_f32 v[34:35], v[34:35], v[70:71] op_sel_hi:[1,0]
	v_pk_mul_f32 v[48:49], v[48:49], v[72:73] op_sel_hi:[1,0]
	v_pk_mul_f32 v[50:51], v[50:51], v[72:73] op_sel_hi:[1,0]
	v_pk_fma_f32 v[34:35], v[2:3], v[34:35], v[6:7]
	v_pk_fma_f32 v[32:33], v[0:1], v[32:33], v[4:5]
	v_pk_fma_f32 v[2:3], v[2:3], v[50:51], v[6:7]
	v_pk_fma_f32 v[0:1], v[0:1], v[48:49], v[4:5]
	flat_store_dwordx4 v[12:13], v[32:35] nt
	flat_store_dwordx4 v[30:31], v[0:3] nt
	flat_load_dwordx4 v[0:3], v[22:23] offset:1024
	s_nop 0
	flat_load_dwordx4 v[4:7], v[24:25] offset:1024
	v_pk_mul_f32 v[32:33], v[38:39], v[70:71] op_sel_hi:[1,0]
	v_pk_mul_f32 v[30:31], v[36:37], v[70:71] op_sel_hi:[1,0]
	v_pk_mul_f32 v[34:35], v[54:55], v[72:73] op_sel_hi:[1,0]
	v_pk_mul_f32 v[36:37], v[52:53], v[72:73] op_sel_hi:[1,0]
	s_waitcnt vmcnt(0) lgkmcnt(0)
	v_pk_fma_f32 v[30:31], v[30:31], v[0:1], v[4:5]
	v_pk_fma_f32 v[32:33], v[32:33], v[2:3], v[6:7]
	v_pk_fma_f32 v[0:1], v[0:1], v[36:37], v[4:5]
	v_pk_fma_f32 v[2:3], v[2:3], v[34:35], v[6:7]
	flat_store_dwordx4 v[12:13], v[30:33] offset:1024 nt
	flat_store_dwordx4 v[28:29], v[0:3] nt
	flat_load_dwordx4 v[0:3], v[22:23] offset:2048
	s_nop 0
	flat_load_dwordx4 v[4:7], v[24:25] offset:2048
	v_pk_mul_f32 v[30:31], v[42:43], v[70:71] op_sel_hi:[1,0]
	v_pk_mul_f32 v[28:29], v[40:41], v[70:71] op_sel_hi:[1,0]
	v_pk_mul_f32 v[32:33], v[58:59], v[72:73] op_sel_hi:[1,0]
	v_pk_mul_f32 v[34:35], v[56:57], v[72:73] op_sel_hi:[1,0]
	s_waitcnt vmcnt(0) lgkmcnt(0)
	v_pk_fma_f32 v[28:29], v[28:29], v[0:1], v[4:5]
	v_pk_fma_f32 v[30:31], v[30:31], v[2:3], v[6:7]
	v_pk_fma_f32 v[0:1], v[0:1], v[34:35], v[4:5]
	v_pk_fma_f32 v[2:3], v[2:3], v[32:33], v[6:7]
	flat_store_dwordx4 v[12:13], v[28:31] offset:2048 nt
	flat_store_dwordx4 v[26:27], v[0:3] nt
	flat_load_dwordx4 v[0:3], v[22:23] offset:3072
	s_nop 0
	flat_load_dwordx4 v[4:7], v[24:25] offset:3072
	v_pk_mul_f32 v[28:29], v[46:47], v[70:71] op_sel_hi:[1,0]
	v_pk_mul_f32 v[26:27], v[44:45], v[70:71] op_sel_hi:[1,0]
	v_pk_mul_f32 v[30:31], v[62:63], v[72:73] op_sel_hi:[1,0]
	v_pk_mul_f32 v[32:33], v[60:61], v[72:73] op_sel_hi:[1,0]
	s_waitcnt vmcnt(0) lgkmcnt(0)
	v_pk_fma_f32 v[26:27], v[26:27], v[0:1], v[4:5]
	v_pk_fma_f32 v[28:29], v[28:29], v[2:3], v[6:7]
	v_pk_fma_f32 v[0:1], v[0:1], v[32:33], v[4:5]
	v_pk_fma_f32 v[2:3], v[2:3], v[30:31], v[6:7]
	flat_store_dwordx4 v[12:13], v[26:29] offset:3072 nt
	flat_store_dwordx4 v[14:15], v[0:3] nt
	s_cbranch_scc0 .LBB0_1048
	s_add_i32 s2, s2, s42
	s_add_u32 s8, s8, s10
	s_addc_u32 s9, s9, s11
	s_add_u32 s12, s12, s14
	s_addc_u32 s13, s13, s15
	s_add_u32 s16, s16, s14
	s_addc_u32 s17, s17, s15
	s_add_u32 s18, s18, s14
	s_addc_u32 s19, s19, s15
	s_add_u32 s20, s20, s14
	s_addc_u32 s21, s21, s15
	s_add_u32 s22, s22, s14
	s_addc_u32 s23, s23, s15
	s_cmpk_gt_i32 s2, 0x1ff
	s_waitcnt lgkmcnt(0)
	s_barrier
	s_cbranch_scc0 .LBB0_1031
